# code prefetch issued by one workgroup in sixteen (2 per XCD)
# baseline (speedup 1.0000x reference)
_Z12trunk_kernel2KP:
	s_and_b32 s18, s2, 0x78
	s_cmp_lg_u32 s18, 0
	s_cbranch_scc1 .Lent_nopf
	s_getpc_b64 s[18:19]
	v_and_b32_e32 v254, 0x3ff, v0
	v_lshlrev_b32_e32 v254, 6, v254
	global_load_dword v255, v254, s[18:19]

.Lxb_pf_0:
	v_readlane_b32 s18, v252, 5
	s_nop 3
	s_and_b32 s18, s18, 0x78
	s_cmp_lg_u32 s18, 0
	s_cbranch_scc1 .Lxb_wait_0
	s_getpc_b64 s[18:19]
	s_mov_b64 s[22:23], exec
	s_mov_b64 exec, -1
	v_mbcnt_lo_u32_b32 v254, -1, 0
	v_mbcnt_hi_u32_b32 v254, -1, v254
	v_lshlrev_b32_e32 v254, 7, v254
	global_load_dword v255, v254, s[18:19]
	s_add_u32 s18, s18, 0x2000
	s_addc_u32 s19, s19, 0
	global_load_dword v255, v254, s[18:19]
	s_add_u32 s18, s18, 0x2000
	s_addc_u32 s19, s19, 0
	global_load_dword v255, v254, s[18:19]
	s_add_u32 s18, s18, 0x2000
	s_addc_u32 s19, s19, 0
	global_load_dword v255, v254, s[18:19]
	s_mov_b64 exec, s[22:23]

.Lxb_pf_12:
	v_readlane_b32 s18, v252, 5
	s_nop 3
	s_and_b32 s18, s18, 0x78
	s_cmp_lg_u32 s18, 0
	s_cbranch_scc1 .Lxb_wait_12
	s_getpc_b64 s[18:19]
	s_mov_b64 s[22:23], exec
	s_mov_b64 exec, -1
	v_mbcnt_lo_u32_b32 v254, -1, 0
	v_mbcnt_hi_u32_b32 v254, -1, v254
	v_lshlrev_b32_e32 v254, 7, v254
	global_load_dword v255, v254, s[18:19]
	s_add_u32 s18, s18, 0x2000
	s_addc_u32 s19, s19, 0
	global_load_dword v255, v254, s[18:19]
	s_add_u32 s18, s18, 0x2000
	s_addc_u32 s19, s19, 0
	global_load_dword v255, v254, s[18:19]
	s_mov_b64 exec, s[22:23]

.Lxb_pf_13:
	v_readlane_b32 s18, v252, 5
	s_nop 3
	s_and_b32 s18, s18, 0x78
	s_cmp_lg_u32 s18, 0
	s_cbranch_scc1 .Lxb_wait_13
	s_getpc_b64 s[18:19]
	s_mov_b64 s[22:23], exec
	s_mov_b64 exec, -1
	v_mbcnt_lo_u32_b32 v254, -1, 0
	v_mbcnt_hi_u32_b32 v254, -1, v254
	v_lshlrev_b32_e32 v254, 7, v254
	global_load_dword v255, v254, s[18:19]
	s_mov_b64 exec, s[22:23]

.Lxb_pf_14:
	v_readlane_b32 s18, v252, 5
	s_nop 3
	s_and_b32 s18, s18, 0x78
	s_cmp_lg_u32 s18, 0
	s_cbranch_scc1 .Lxb_wait_14
	s_getpc_b64 s[18:19]
	s_mov_b64 s[22:23], exec
	s_mov_b64 exec, -1
	v_mbcnt_lo_u32_b32 v254, -1, 0
	v_mbcnt_hi_u32_b32 v254, -1, v254
	v_lshlrev_b32_e32 v254, 6, v254
	global_load_dword v255, v254, s[18:19]
	s_mov_b64 exec, s[22:23]
